# dt fold (spread) + P4: leftover V^T tiles 24..39 moved from workgroups 0..15 (64-chunk scans) to 176..191 (32-chunk scans)
# baseline (speedup 1.0000x reference)
.LBB0_1496:
	s_mul_hi_u32 s2, s41, 0xe8
	s_mul_i32 s2, s2, s39
	s_sub_i32 s2, 0xe8, s2
	s_sub_i32 s3, s2, s39
	s_cmp_ge_u32 s2, s39
	s_cselect_b32 s2, s3, s2
	s_sub_i32 s3, s2, s39
	s_cmp_ge_u32 s2, s39
	s_cselect_b32 s2, s3, s2
	s_sub_i32 s2, s40, s2
	s_ashr_i32 s3, s2, 31
	s_abs_i32 s2, s2
	s_mul_hi_u32 s4, s2, s41
	s_mul_i32 s4, s4, s39
	s_sub_i32 s2, s2, s4
	s_sub_i32 s4, s2, s39
	s_cmp_ge_u32 s2, s39
	s_cselect_b32 s2, s4, s2
	s_sub_i32 s4, s2, s39
	s_cmp_ge_u32 s2, s39
	s_cselect_b32 s2, s4, s2
	s_xor_b32 s2, s2, s3
	s_sub_i32 s28, s2, s3
	s_cmp_lt_u32 s89, 16
	s_cselect_b32 s28, 0x3e8, s28
	s_sub_u32 s2, s89, 0xb0
	s_cmp_lt_u32 s2, 16
	s_cbranch_scc0 .Lkvm_n
	s_add_u32 s28, s2, 24
.Lkvm_n:
	s_cmp_gt_i32 s28, 39
	v_readfirstlane_b32 s9, v182
	s_cbranch_scc1 .LBB0_1512
	v_readlane_b32 s12, v244, 0
	v_readlane_b32 s16, v244, 4
	v_readlane_b32 s17, v244, 5
	v_readlane_b32 s18, v244, 6
	v_readlane_b32 s19, v244, 7
	s_mov_b64 s[4:5], s[16:17]
	s_mov_b64 s[6:7], s[18:19]
	s_add_u32 s29, s6, 0x1f600000
	s_addc_u32 s30, s7, 0
	s_ashr_i32 s34, s28, 31
	s_lshr_b32 s2, s34, 29
	s_add_i32 s2, s28, s2
	s_lshr_b32 s6, s9, 6
	s_ashr_i32 s3, s2, 3
	s_and_b32 s2, s2, -8
	s_lshr_b32 s10, s9, 8
	s_lshl_b32 s31, s6, 10
	s_sub_i32 s2, s28, s2
	s_cmp_lt_i32 s2, 0
	s_cselect_b32 s4, 6, 5
	s_mul_i32 s2, s2, s4
	s_add_i32 s2, s2, s3
	s_mul_hi_i32 s3, s2, 0x66666667
	s_lshr_b32 s4, s3, 31
	s_ashr_i32 s3, s3, 5
	s_add_i32 s3, s3, s4
	s_lshl_b32 s4, s3, 3
	s_sub_i32 s5, 4, s4
	s_min_u32 s5, s5, 8
	s_mulk_i32 s3, 0x50
	s_sub_i32 s7, s2, s3
	v_cvt_f32_ubyte0_e32 v1, s5
	v_cvt_f32_i32_e32 v0, s7
	v_rcp_iflag_f32_e32 v2, v1
	s_ashr_i32 s2, s7, 30
	s_or_b32 s8, s2, 1
	v_mov_b32_e32 v137, 0
	v_mul_f32_e32 v2, v0, v2
	v_trunc_f32_e32 v2, v2
	v_fma_f32 v0, -v2, v1, v0
	v_cvt_i32_f32_e32 v2, v2
	v_cmp_ge_f32_e64 s[2:3], |v0|, v1
	s_and_b64 s[2:3], s[2:3], exec
	s_cselect_b32 s2, s8, 0
	v_readfirstlane_b32 s3, v2
	s_add_i32 s8, s3, s2
	s_mul_i32 s2, s8, s5
	s_sub_i32 s2, s7, s2
	s_sext_i32_i8 s2, s2
	s_add_i32 s20, s4, s2
	s_ashr_i32 s21, s20, 31
	s_bfe_i64 s[4:5], s[8:9], 0x80000
	s_lshl_b64 s[2:3], s[20:21], 19
	s_lshl_b64 s[4:5], s[4:5], 19
	s_add_u32 s24, s33, s4
	s_addc_u32 s25, s38, s5
	s_add_i32 s35, s31, 0
	s_add_i32 m0, s35, 0x10000
	v_mov_b32_e32 v131, v137
	global_load_lds_dwordx4 v130, s[24:25]
	s_add_i32 m0, s35, 0x12000
	s_add_u32 s4, s24, 0x40000
	global_load_lds_dwordx4 v134, s[24:25]
	s_addc_u32 s5, s25, 0
	s_add_i32 m0, s35, 0x14000
	v_mov_b32_e32 v135, v137
	global_load_lds_dwordx4 v130, s[4:5]
	s_add_i32 m0, s35, 0x16000
	s_add_u32 s22, s29, s2
	s_addc_u32 s23, s30, s3
	s_add_i32 s36, s35, 0x2000
	global_load_lds_dwordx4 v134, s[4:5]
	s_mov_b32 m0, s35
	s_add_u32 s2, s22, 0x40000
	global_load_lds_dwordx4 v128, s[22:23]
	s_mov_b32 m0, s36
	s_addc_u32 s3, s23, 0
	s_add_i32 s37, s35, 0x4000
	global_load_lds_dwordx4 v132, s[22:23]
	s_mov_b32 m0, s37
	s_add_i32 s39, s35, 0x6000
	global_load_lds_dwordx4 v128, s[2:3]
	s_mov_b32 m0, s39
	v_mov_b32_e32 v129, v137
	global_load_lds_dwordx4 v132, s[2:3]
	v_mov_b32_e32 v133, v137
	s_cmp_eq_u32 s10, 1
	s_mov_b32 s40, 0
	v_lshl_add_u64 v[6:7], s[24:25], 0, v[130:131]
	v_lshl_add_u64 v[4:5], s[24:25], 0, v[134:135]
	v_lshl_add_u64 v[0:1], s[22:23], 0, v[128:129]
	s_cselect_b64 s[2:3], -1, 0
	s_cmp_lg_u32 s10, 1
	v_lshl_add_u64 v[2:3], s[22:23], 0, v[132:133]
	v_readlane_b32 s13, v244, 1
	v_readlane_b32 s14, v244, 2
	v_readlane_b32 s15, v244, 3
	s_cbranch_scc1 .LBB0_1499
	s_barrier
